# GEMM phase prologues: K-tile-1 staging loads issued before the first wait (14 loads in flight during the pipeline fill instead of 8 then 6)
# baseline (speedup 1.0000x reference)
; #define PG8_STAGE(bufoff, gbase, voff) do { _Pragma("unroll") for (int _i = 0; _i < 2; ++_i) \
;         __builtin_amdgcn_global_load_lds((const unsigned*)((const char*)(gbase) + (voff)[_i]), (PG8_LAS unsigned*)(lds + (bufoff) + ldsw + _i * 8192), 16, 0, 0); } while (0)
; #define PG8_WAIT_V(n) asm volatile("s_waitcnt vmcnt(" #n ")" ::: "memory")
; #define PG8_BAR __builtin_amdgcn_s_barrier()
; template <class Epi, class Sched, bool ALIGN_EPI = false, bool SP2 = false, bool HALFM = false>
; __device__ __forceinline__ void gemm_phase(PG8_LAS unsigned char* lds, const Gemm g, const Sched& S, const Epi& E) {
;     ...
;     if constexpr (SP2) {
;         PG8_STAGE(PG8_SB(0, 0), cB, voffB); PG8_STAGE(PG8_SB(0, 1), cB + hstep, voffB); PG8_STAGE(PG8_SA(0, 0), cA, voffA); PG8_STAGE(PG8_SA(0, 1), cA + hstep, voffA);
;         if (wr == 1) PG8_BAR;
;         PG8_WAIT_V(2); PG8_BAR;
;         PG8_STAGE(PG8_SB(1, 0), cB + kstep, voffB); PG8_STAGE(PG8_SA(1, 0), cA + kstep, voffA); PG8_STAGE(PG8_SB(1, 1), cB + hstep + kstep, voffB);
;         PG8_WAIT_V(6); PG8_BAR;
.LBB0_172:
	v_readlane_b32 s22, v254, 5
	s_lshl_b32 s5, s5, 5
	v_mov_b32_e32 v131, v81
	v_readlane_b32 s23, v254, 6
	s_and_b32 s12, s5, 0x60
	s_add_i32 m0, s47, 0x18000
	v_lshl_add_u64 v[0:1], v[0:1], 0, s[82:83]
	v_lshl_add_u64 v[12:13], s[22:23], 0, v[130:131]
	v_mov_b32_e32 v133, v81
	s_lshl_b32 s9, s8, 13
	s_lshl_b32 s5, s12, 7
	global_load_lds_dwordx4 v[0:1], off
	v_lshl_add_u64 v[0:1], v[2:3], 0, s[82:83]
	s_add_i32 m0, s47, 0x1a000
	s_add_i32 s51, s47, 0x8000
	s_add_i32 s52, s47, 0xa000
	v_lshl_add_u64 v[14:15], s[22:23], 0, v[132:133]
	global_load_lds_dwordx4 v[0:1], off
	v_lshl_add_u64 v[0:1], v[12:13], 0, s[82:83]
	s_mov_b32 m0, s51
	s_add_u32 s10, s24, 0x40080
	global_load_lds_dwordx4 v[0:1], off
	v_lshl_add_u64 v[0:1], v[14:15], 0, s[82:83]
	s_mov_b32 m0, s52
	s_addc_u32 s11, s25, 0
	global_load_lds_dwordx4 v[0:1], off
	s_add_i32 m0, s47, 0x1c000
	v_lshl_add_u64 v[0:1], s[10:11], 0, v[80:81]
	global_load_lds_dwordx4 v[0:1], off
	v_lshl_add_u64 v[0:1], s[10:11], 0, v[134:135]
	s_add_i32 m0, s47, 0x1e000
	s_cmpk_lt_u32 s4, 0x100
	global_load_lds_dwordx4 v[0:1], off
	s_waitcnt vmcnt(8)
	s_barrier
	v_lshrrev_b32_e32 v1, 1, v4
	v_and_b32_e32 v1, 24, v1
	v_and_b32_e32 v0, 15, v4
	v_lshlrev_b32_e32 v2, 1, v1
	v_lshl_or_b32 v142, s8, 6, v0
	v_lshl_or_b32 v2, v0, 6, v2
	v_lshlrev_b32_e32 v0, 2, v0
	v_and_b32_e32 v3, 32, v0
	v_bitop3_b32 v143, v2, s5, v3 bitop3:0xde
	s_cselect_b64 s[4:5], -1, 0
	s_lshl_b32 s8, s8, 8
	s_add_i32 s8, s8, 0
	s_add_i32 s8, s8, 0x24900
	v_add_u32_e32 v145, s8, v0
	v_lshlrev_b32_e32 v0, 14, v5
	v_and_b32_e32 v0, 0xffff8000, v0
	v_or_b32_e32 v144, s12, v1
	v_lshl_add_u32 v0, v6, 11, v0
	v_and_b32_e32 v1, 1, v5
	v_lshl_or_b32 v0, v1, 6, v0
	v_lshl_add_u32 v136, v7, 1, v0
	v_lshlrev_b32_e32 v0, 14, v8
	v_and_b32_e32 v0, 0xffff8000, v0
	s_waitcnt vmcnt(6)
	v_lshl_add_u32 v0, v9, 11, v0
	v_and_b32_e32 v1, 1, v8
	v_bitop3_b32 v4, v2, s9, v3 bitop3:0xde
	v_lshl_or_b32 v0, v1, 6, v0
	v_readlane_b32 s8, v254, 2
	v_mov_b32_e32 v137, v81
	v_lshl_add_u32 v138, v10, 1, v0
	v_mov_b32_e32 v139, v81
	s_mov_b32 s55, 0
	v_add_u32_e32 v146, 0, v4
	v_readlane_b32 s56, v253, 63
	s_mov_b32 s57, s8
	s_mov_b32 s53, 0
	s_barrier
	v_readlane_b32 s9, v254, 3
	s_branch .LBB0_175

; #define PG8_STAGE(bufoff, gbase, voff) do { _Pragma("unroll") for (int _i = 0; _i < 2; ++_i) \
;         __builtin_amdgcn_global_load_lds((const unsigned*)((const char*)(gbase) + (voff)[_i]), (PG8_LAS unsigned*)(lds + (bufoff) + ldsw + _i * 8192), 16, 0, 0); } while (0)
; #define PG8_WAIT_V(n) asm volatile("s_waitcnt vmcnt(" #n ")" ::: "memory")
; #define PG8_BAR __builtin_amdgcn_s_barrier()
; template <class Epi, class Sched, bool ALIGN_EPI = false, bool SP2 = false, bool HALFM = false>
; __device__ __forceinline__ void gemm_phase(PG8_LAS unsigned char* lds, const Gemm g, const Sched& S, const Epi& E) {
;     ...
;     if constexpr (SP2) {
;         PG8_STAGE(PG8_SB(0, 0), cB, voffB); PG8_STAGE(PG8_SB(0, 1), cB + hstep, voffB); PG8_STAGE(PG8_SA(0, 0), cA, voffA); PG8_STAGE(PG8_SA(0, 1), cA + hstep, voffA);
;         if (wr == 1) PG8_BAR;
;         PG8_WAIT_V(2); PG8_BAR;
;         PG8_STAGE(PG8_SB(1, 0), cB + kstep, voffB); PG8_STAGE(PG8_SA(1, 0), cA + kstep, voffA); PG8_STAGE(PG8_SB(1, 1), cB + hstep + kstep, voffB);
;         PG8_WAIT_V(6); PG8_BAR;
.LBB0_266:
	v_readlane_b32 s6, v254, 55
	v_bfe_u32 v13, v12, 4, 2
	v_readlane_b32 s20, v254, 13
	s_cmp_eq_u32 s73, 0
	v_readlane_b32 s7, v254, 56
	s_waitcnt vmcnt(0)
	v_and_b32_e32 v18, 15, v12
	v_lshlrev_b32_e32 v20, 4, v13
	v_lshlrev_b32_e32 v12, 2, v12
	v_mov_b32_e32 v165, v81
	v_readlane_b32 s21, v254, 14
	s_cselect_b32 s11, s7, 0
	s_cselect_b32 s10, s6, 0
	s_and_b32 s51, s12, 3
	v_lshl_or_b32 v202, s9, 6, v18
	v_lshl_or_b32 v18, v18, 6, v20
	s_lshl_b32 s6, s9, 13
	v_and_b32_e32 v12, 32, v12
	s_add_i32 m0, s46, 0x18000
	v_lshl_add_u64 v[0:1], v[0:1], 0, s[82:83]
	v_lshl_add_u64 v[14:15], s[20:21], 0, v[164:165]
	v_mov_b32_e32 v163, v81
	v_bitop3_b32 v20, v18, s6, v12 bitop3:0xde
	s_lshl_b32 s6, s51, 12
	global_load_lds_dwordx4 v[0:1], off
	v_lshl_add_u64 v[0:1], v[2:3], 0, s[82:83]
	s_add_i32 m0, s46, 0x1a000
	s_add_i32 s52, s46, 0x8000
	s_add_i32 s53, s46, 0xa000
	v_lshl_add_u64 v[16:17], s[20:21], 0, v[162:163]
	v_bitop3_b32 v203, v18, s6, v12 bitop3:0xde
	global_load_lds_dwordx4 v[0:1], off
	v_lshl_add_u64 v[0:1], v[14:15], 0, s[82:83]
	s_mov_b32 m0, s52
	s_add_u32 s6, s22, 0xb0080
	global_load_lds_dwordx4 v[0:1], off
	v_lshl_add_u64 v[0:1], v[16:17], 0, s[82:83]
	s_mov_b32 m0, s53
	s_addc_u32 s7, s23, 0
	global_load_lds_dwordx4 v[0:1], off
	s_add_i32 m0, s46, 0x1c000
	v_lshl_add_u64 v[0:1], s[6:7], 0, v[80:81]
	global_load_lds_dwordx4 v[0:1], off
	v_lshl_add_u64 v[0:1], s[6:7], 0, v[160:161]
	s_add_i32 m0, s46, 0x1e000
	s_movk_i32 s16, 0xb00
	global_load_lds_dwordx4 v[0:1], off
	s_waitcnt vmcnt(8)
	s_barrier
	v_lshrrev_b32_e32 v1, 1, v9
	v_mul_lo_u32 v0, v8, s16
	s_mov_b32 s17, 0xb000
	s_cmpk_lt_u32 s8, 0x100
	v_mad_u64_u32 v[0:1], s[8:9], v1, s17, v[0:1]
	v_or_b32_e32 v0, v0, v10
	v_add_lshl_u32 v0, v0, v11, 1
	v_mov_b32_e32 v1, v81
	s_mov_b64 s[18:19], 0xb0080
	v_lshl_add_u64 v[166:167], v[0:1], 0, s[18:19]
	v_lshrrev_b32_e32 v1, 1, v4
	v_mul_lo_u32 v0, v5, s16
	v_mad_u64_u32 v[0:1], s[8:9], v1, s17, v[0:1]
	s_waitcnt vmcnt(6)
	v_or_b32_e32 v0, v0, v6
	v_lshlrev_b32_e32 v19, 3, v13
	s_cselect_b64 s[12:13], -1, 0
	s_cmp_lg_u64 s[10:11], 0
	v_add_lshl_u32 v0, v0, v7, 1
	v_mov_b32_e32 v1, v81
	v_readlane_b32 s8, v254, 28
	s_mov_b32 s50, 0
	v_lshl_or_b32 v204, s51, 5, v19
	v_cmp_eq_u32_e64 s[6:7], 0, v13
	s_cselect_b64 s[14:15], -1, 0
	v_lshl_add_u64 v[168:169], v[0:1], 0, s[18:19]
	v_add_u32_e32 v205, 0, v20
	v_readlane_b32 s56, v254, 9
	s_mov_b32 s57, s8
	s_barrier
	v_readlane_b32 s9, v254, 29
	s_branch .LBB0_269

; #define PG8_STAGE(bufoff, gbase, voff) do { _Pragma("unroll") for (int _i = 0; _i < 2; ++_i) \
;         __builtin_amdgcn_global_load_lds((const unsigned*)((const char*)(gbase) + (voff)[_i]), (PG8_LAS unsigned*)(lds + (bufoff) + ldsw + _i * 8192), 16, 0, 0); } while (0)
; #define PG8_WAIT_V(n) asm volatile("s_waitcnt vmcnt(" #n ")" ::: "memory")
; #define PG8_BAR __builtin_amdgcn_s_barrier()
; template <class Epi, class Sched, bool ALIGN_EPI = false, bool SP2 = false, bool HALFM = false>
; __device__ __forceinline__ void gemm_phase(PG8_LAS unsigned char* lds, const Gemm g, const Sched& S, const Epi& E) {
;     ...
;     if constexpr (SP2) {
;         PG8_STAGE(PG8_SB(0, 0), cB, voffB); PG8_STAGE(PG8_SB(0, 1), cB + hstep, voffB); PG8_STAGE(PG8_SA(0, 0), cA, voffA); PG8_STAGE(PG8_SA(0, 1), cA + hstep, voffA);
;         if (wr == 1) PG8_BAR;
;         PG8_WAIT_V(2); PG8_BAR;
;         PG8_STAGE(PG8_SB(1, 0), cB + kstep, voffB); PG8_STAGE(PG8_SA(1, 0), cA + kstep, voffA); PG8_STAGE(PG8_SB(1, 1), cB + hstep + kstep, voffB);
;         PG8_WAIT_V(6); PG8_BAR;
.LBB0_406:
	v_and_b32_e32 v11, 15, v4
	v_bfe_u32 v4, v4, 4, 2
	v_lshlrev_b32_e32 v17, 4, v4
	v_readlane_b32 s24, v254, 22
	v_lshl_or_b32 v178, s0, 6, v11
	v_lshl_or_b32 v17, v11, 6, v17
	v_lshlrev_b32_e32 v11, 2, v11
	v_mov_b32_e32 v147, v81
	v_readlane_b32 s25, v254, 23
	s_and_b32 s1, s1, 3
	s_lshl_b32 s5, s0, 13
	v_and_b32_e32 v18, 32, v11
	s_add_i32 m0, s49, 0x18000
	v_lshl_add_u64 v[0:1], v[0:1], 0, s[82:83]
	v_lshl_add_u64 v[12:13], s[24:25], 0, v[146:147]
	v_mov_b32_e32 v149, v81
	v_bitop3_b32 v19, v17, s5, v18 bitop3:0xde
	s_lshl_b32 s5, s1, 12
	global_load_lds_dwordx4 v[0:1], off
	v_lshl_add_u64 v[0:1], v[2:3], 0, s[82:83]
	s_add_i32 m0, s49, 0x1a000
	s_add_i32 s53, s49, 0x8000
	s_add_i32 s54, s49, 0xa000
	v_lshl_add_u64 v[14:15], s[24:25], 0, v[148:149]
	global_load_lds_dwordx4 v[0:1], off
	v_lshl_add_u64 v[0:1], v[12:13], 0, s[82:83]
	s_mov_b32 m0, s53
	s_add_u32 s8, s26, 0x40080
	global_load_lds_dwordx4 v[0:1], off
	v_lshl_add_u64 v[0:1], v[14:15], 0, s[82:83]
	s_mov_b32 m0, s54
	s_addc_u32 s9, s27, 0
	global_load_lds_dwordx4 v[0:1], off
	s_add_i32 m0, s49, 0x1c000
	v_lshl_add_u64 v[0:1], s[8:9], 0, v[80:81]
	global_load_lds_dwordx4 v[0:1], off
	v_lshl_add_u64 v[0:1], s[8:9], 0, v[150:151]
	s_add_i32 m0, s49, 0x1e000
	s_cmpk_lt_u32 s4, 0x100
	global_load_lds_dwordx4 v[0:1], off
	s_waitcnt vmcnt(8)
	s_barrier
	v_lshlrev_b32_e32 v0, 14, v5
	v_and_b32_e32 v0, 0xffff8000, v0
	v_lshl_add_u32 v0, v6, 11, v0
	v_and_b32_e32 v1, 1, v5
	s_cselect_b64 s[8:9], -1, 0
	s_bitcmp0_b32 s4, 6
	v_lshl_or_b32 v0, v1, 6, v0
	s_cselect_b64 s[10:11], -1, 0
	s_lshl_b32 s0, s0, 8
	v_lshl_add_u32 v162, v7, 1, v0
	v_lshlrev_b32_e32 v0, 14, v8
	s_add_i32 s0, s0, 0
	v_and_b32_e32 v0, 0xffff8000, v0
	v_lshlrev_b32_e32 v16, 3, v4
	s_waitcnt vmcnt(6)
	v_cmp_eq_u32_e32 vcc, 0, v4
	s_add_i32 s0, s0, 0x24900
	v_lshl_add_u32 v0, v9, 11, v0
	v_and_b32_e32 v1, 1, v8
	v_cndmask_b32_e64 v152, 1.0, -1.0, vcc
	v_lshl_or_b32 v180, s1, 5, v16
	v_add_u32_e32 v181, s0, v11
	v_lshl_or_b32 v0, v1, 6, v0
	v_readlane_b32 s0, v254, 19
	v_bitop3_b32 v179, v17, s5, v18 bitop3:0xde
	s_mov_b32 s57, 0
	v_cmp_gt_u32_e64 s[4:5], 2, v4
	v_mov_b32_e32 v153, v152
	v_mov_b32_e32 v160, v152
	v_mov_b32_e32 v161, v152
	v_mov_b32_e32 v163, v81
	v_lshl_add_u32 v164, v10, 1, v0
	v_mov_b32_e32 v165, v81
	v_add_u32_e32 v182, 0, v19
	v_readlane_b32 s59, v254, 10
	s_mov_b32 s58, s0
	s_mov_b32 s55, 0
	s_barrier
	v_readlane_b32 s1, v254, 20
	s_branch .LBB0_409

; #define PG8_STAGE(bufoff, gbase, voff) do { _Pragma("unroll") for (int _i = 0; _i < 2; ++_i) \
;         __builtin_amdgcn_global_load_lds((const unsigned*)((const char*)(gbase) + (voff)[_i]), (PG8_LAS unsigned*)(lds + (bufoff) + ldsw + _i * 8192), 16, 0, 0); } while (0)
; #define PG8_WAIT_V(n) asm volatile("s_waitcnt vmcnt(" #n ")" ::: "memory")
; #define PG8_BAR __builtin_amdgcn_s_barrier()
; template <class Epi, class Sched, bool ALIGN_EPI = false, bool SP2 = false, bool HALFM = false>
; __device__ __forceinline__ void gemm_phase(PG8_LAS unsigned char* lds, const Gemm g, const Sched& S, const Epi& E) {
;     ...
;     if constexpr (SP2) {
;         PG8_STAGE(PG8_SB(0, 0), cB, voffB); PG8_STAGE(PG8_SB(0, 1), cB + hstep, voffB); PG8_STAGE(PG8_SA(0, 0), cA, voffA); PG8_STAGE(PG8_SA(0, 1), cA + hstep, voffA);
;         if (wr == 1) PG8_BAR;
;         PG8_WAIT_V(2); PG8_BAR;
;         PG8_STAGE(PG8_SB(1, 0), cB + kstep, voffB); PG8_STAGE(PG8_SA(1, 0), cA + kstep, voffA); PG8_STAGE(PG8_SB(1, 1), cB + hstep + kstep, voffB);
;         PG8_WAIT_V(6); PG8_BAR;
.LBB0_1155:
	s_waitcnt vmcnt(0)
	v_bfe_u32 v16, v6, 4, 2
	v_and_b32_e32 v7, 15, v6
	v_lshlrev_b32_e32 v18, 4, v16
	v_lshlrev_b32_e32 v6, 2, v6
	s_and_b32 s46, s4, 3
	v_lshl_or_b32 v188, s1, 6, v7
	v_lshl_or_b32 v7, v7, 6, v18
	s_lshl_b32 s1, s1, 13
	v_and_b32_e32 v6, 32, v6
	v_lshl_add_u64 v[8:9], s[20:21], 0, v[80:81]
	v_mov_b32_e32 v161, v81
	v_readlane_b32 s18, v254, 33
	v_bitop3_b32 v18, v7, s1, v6 bitop3:0xde
	s_lshl_b32 s1, s46, 12
	v_lshl_add_u64 v[10:11], s[20:21], 0, v[160:161]
	v_mov_b32_e32 v165, v81
	v_readlane_b32 s19, v254, 34
	v_bitop3_b32 v189, v7, s1, v6 bitop3:0xde
	s_add_i32 m0, s27, 0x18000
	v_lshl_add_u64 v[6:7], v[8:9], 0, s[82:83]
	v_lshl_add_u64 v[12:13], s[18:19], 0, v[164:165]
	v_mov_b32_e32 v163, v81
	global_load_lds_dwordx4 v[6:7], off
	v_lshl_add_u64 v[6:7], v[10:11], 0, s[82:83]
	s_add_i32 m0, s27, 0x1a000
	s_add_i32 s47, s27, 0x8000
	s_add_i32 s48, s27, 0xa000
	v_lshl_add_u64 v[14:15], s[18:19], 0, v[162:163]
	global_load_lds_dwordx4 v[6:7], off
	v_lshl_add_u64 v[6:7], v[12:13], 0, s[82:83]
	s_mov_b32 m0, s47
	s_add_u32 s4, s20, 0x40080
	global_load_lds_dwordx4 v[6:7], off
	v_lshl_add_u64 v[6:7], v[14:15], 0, s[82:83]
	s_mov_b32 m0, s48
	s_addc_u32 s5, s21, 0
	global_load_lds_dwordx4 v[6:7], off
	s_add_i32 m0, s27, 0x1c000
	v_lshl_add_u64 v[6:7], s[4:5], 0, v[80:81]
	global_load_lds_dwordx4 v[6:7], off
	v_lshl_add_u64 v[6:7], s[4:5], 0, v[160:161]
	s_add_i32 m0, s27, 0x1e000
	v_lshlrev_b32_e32 v17, 3, v16
	global_load_lds_dwordx4 v[6:7], off
	s_waitcnt vmcnt(8)
	s_barrier
	v_lshlrev_b32_e32 v6, 14, v4
	v_and_b32_e32 v6, 0xffff8000, v6
	v_lshl_add_u32 v3, v3, 11, v6
	v_and_b32_e32 v4, 1, v4
	v_lshl_or_b32 v3, v4, 6, v3
	v_lshl_add_u32 v166, v5, 1, v3
	v_lshlrev_b32_e32 v3, 14, v0
	v_and_b32_e32 v3, 0xffff8000, v3
	s_waitcnt vmcnt(6)
	v_lshl_add_u32 v1, v1, 11, v3
	v_and_b32_e32 v0, 1, v0
	s_cmpk_lt_u32 s0, 0x100
	v_lshl_or_b32 v0, v0, 6, v1
	v_readlane_b32 s4, v254, 28
	v_lshl_or_b32 v202, s46, 5, v17
	s_cselect_b64 s[8:9], -1, 0
	s_mov_b32 s49, 0
	v_cmp_eq_u32_e64 s[0:1], 0, v16
	v_mov_b32_e32 v167, v81
	v_lshl_add_u32 v168, v2, 1, v0
	v_mov_b32_e32 v169, v81
	v_add_u32_e32 v203, 0, v18
	v_readlane_b32 s50, v254, 9
	s_mov_b32 s51, s4
	s_barrier
	v_readlane_b32 s5, v254, 29
	s_branch .LBB0_1158
